# w_out transposes moved from phase 0 to the 128 lightest phase-3 workgroups; w_mq/w_mo transposes moved to the 64 workgroups idle in phase 1's last round
# speedup vs baseline: 1.2082x; 1.0120x over previous
.LBB0_230:
	v_readlane_b32 s64, v209, 33
	v_readlane_b32 s62, v209, 35
	s_mov_b64 s[40:41], 0
	v_readlane_b32 s60, v209, 37
	v_readlane_b32 s65, v209, 34
	v_readlane_b32 s63, v209, 36
	v_readlane_b32 s61, v209, 38
	s_cmpk_eq_i32 s72, 0x200
	s_cbranch_scc0 .Lp3h_no
	s_sub_i32 s50, s60, 0x100
	s_cmpk_lt_u32 s50, 0x80
	s_cbranch_scc0 .Lp3h_no
	s_add_i32 s50, s50, 0x168
	s_movk_i32 s51, 0x200
	s_movk_i32 s52, 0x1e7
	s_mov_b32 s53, 0
	s_add_u32 s46, s12, 8
	s_addc_u32 s47, s13, 0
	s_branch .Ltramp_p0a
.Lp3h_no:
.LBB0_231:
	s_andn2_b64 vcc, exec, s[40:41]
	s_cbranch_vccnz .LBB0_357
	v_readlane_b32 s20, v210, 49
	v_readlane_b32 s21, v210, 50
	s_andn2_b64 vcc, exec, s[20:21]
	s_mov_b64 s[40:41], -1
	s_cbranch_vccnz .LBB0_235
	v_readlane_b32 s20, v210, 51
	v_readlane_b32 s21, v210, 52
	s_andn2_b64 vcc, exec, s[20:21]
	s_mov_b32 s8, s60
	s_cbranch_vccz .LBB0_259

.LBB0_361:
	s_cmpk_eq_i32 s72, 0x200
	s_cbranch_scc0 .Lp1h_no
	s_sub_i32 s50, s60, 0x1c0
	s_cmpk_lt_u32 s50, 0x40
	s_cbranch_scc0 .Lp1h_no
	s_add_i32 s50, s50, 0x1e8
	s_movk_i32 s51, 0x200
	s_movk_i32 s52, 0x227
	s_mov_b32 s53, 0
	s_add_u32 s46, s12, 8
	s_addc_u32 s47, s13, 0
	s_branch .Lp0_head

.LBB0_362:
	s_andn2_b64 vcc, exec, s[40:41]
	s_cbranch_vccnz .Ltramp7a
	v_readlane_b32 s20, v209, 10
	v_readlane_b32 s21, v209, 11
	s_andn2_b64 vcc, exec, s[20:21]
	s_cbranch_vccnz .Ltramp7a
	s_add_u32 s46, s12, 8
	s_addc_u32 s47, s13, 0
	s_mov_b32 s50, s60
	s_mov_b32 s51, s72
	s_movk_i32 s52, 0xaf0
	s_mov_b32 s53, 0
	s_cmpk_eq_i32 s72, 0x200
	s_cbranch_scc0 .Lp0_head
	s_movk_i32 s52, 0x630
	s_movk_i32 s53, 0x4c0
	s_branch .Lp0_head

.Lp0_head:
	s_mov_b32 s8, s50
	s_cmpk_lt_i32 s50, 0x168
	s_cbranch_scc1 .LBB0_489
	s_add_i32 s8, s50, s53
